# grid barrier: first arriver of each XCD issues an early buffer_wbl2 (on top of the one-poll barrier)
# baseline (speedup 1.0000x reference)
; __device__ __forceinline__ unsigned xb_ld(unsigned* p)              { return __hip_atomic_load(p, __ATOMIC_RELAXED, __HIP_MEMORY_SCOPE_AGENT); }
; __device__ __forceinline__ unsigned xb_add(unsigned* p, unsigned v) { return __hip_atomic_fetch_add(p, v, __ATOMIC_RELAXED, __HIP_MEMORY_SCOPE_AGENT); }
; #define XB_SPIN(cond, bar) do { unsigned _sp = 0; while (cond) { __builtin_amdgcn_s_sleep(1); \
;     if ((++_sp & 255u) == 0u) { if (xb_ld(&(bar)[XB_TMO])) break; if (_sp > XB_SPIN_CAP) { atomicAdd(&(bar)[XB_TMO], 1u); break; } } } } while (0)
; __device__ __forceinline__ void xcd_barrier(const XcdBarrier& b) {
;     ...
;         const unsigned old = xb_add(&bar[XB_XSUB(b.x)], 1u);
;         const unsigned gen = old / nloc;
;         if (old + 1u == (gen + 1u) * nloc) {
;             __builtin_amdgcn_fence(__ATOMIC_RELEASE, "agent");
;             asm volatile("s_waitcnt vmcnt(0)" ::: "memory");
;             const unsigned og = xb_add(&bar[XB_TOP], 1u);
;             const unsigned tg = og / nx;
;             if (og + 1u == (tg + 1u) * nx) xb_add(&bar[XB_TOPGEN], 1u);
;             else XB_SPIN(xb_ld(&bar[XB_TOPGEN]) == tg, bar);
;             __builtin_amdgcn_fence(__ATOMIC_ACQUIRE, "agent");
;             xb_add(&bar[XB_XGEN(b.x)], 1u);
;             asm volatile("s_waitcnt vmcnt(0)" ::: "memory");
;         } else {
;             XB_SPIN(xb_ld(&bar[XB_XGEN(b.x)]) == gen, bar);
.LBB0_590:
	v_readlane_b32 s2, v254, 0
	v_readlane_b32 s3, v254, 1
	v_mov_b32_e32 v1, 1
	v_sub_u32_e32 v4, 0, v2
	s_nop 2
	global_atomic_add v3, v96, v1, s[2:3] sc0
	v_cvt_f32_u32_e32 v1, v2
	v_rcp_iflag_f32_e32 v1, v1
	s_nop 0
	v_mul_f32_e32 v1, 0x4f7ffffe, v1
	v_cvt_u32_f32_e32 v1, v1
	v_mul_lo_u32 v4, v4, v1
	v_mul_hi_u32 v4, v1, v4
	v_add_u32_e32 v1, v1, v4
	s_waitcnt vmcnt(0)
	v_mul_hi_u32 v1, v3, v1
	v_mul_lo_u32 v4, v1, v2
	v_sub_u32_e32 v4, v3, v4
	v_add_u32_e32 v5, 1, v1
	v_cmp_ge_u32_e32 vcc, v4, v2
	v_add_u32_e32 v3, 1, v3
	s_nop 0
	v_cndmask_b32_e32 v1, v1, v5, vcc
	v_sub_u32_e32 v5, v4, v2
	v_cndmask_b32_e32 v4, v4, v5, vcc
	v_add_u32_e32 v5, 1, v1
	v_cmp_ge_u32_e32 vcc, v4, v2
	s_nop 1
	v_cndmask_b32_e32 v1, v1, v5, vcc
	v_mul_lo_u32 v4, v2, v1
	v_add_u32_e32 v2, v4, v2
	v_cmp_ne_u32_e32 vcc, v3, v2
	v_add_u32_e32 v5, 1, v4
	v_cmp_eq_u32_e64 s[10:11], v3, v5
	v_add_u32_e32 v4, 1, v1
	s_waitcnt lgkmcnt(0)
	v_mul_lo_u32 v4, v4, v0
	v_readlane_b32 s2, v254, 4
	v_readlane_b32 s3, v254, 5
	s_nop 4
	s_cbranch_vccnz .Lxb_notlast
	buffer_wbl2 sc1
	s_waitcnt vmcnt(0)
	v_mov_b32_e32 v1, 1
	global_atomic_add v96, v1, s[2:3]
	s_branch .Lxb_poll
.Lxb_notlast:
	s_and_b64 vcc, exec, s[10:11]
	s_cbranch_vccz .Lxb_poll
	buffer_wbl2 sc1
